# grid barrier: everybody waits on the top-level arrival counter reaching (gen+1)*nx (no generation-word bump by the last XCD leader)
# speedup vs baseline: 1.0085x; 1.0032x over previous
; __device__ __forceinline__ unsigned xb_ld(unsigned* p)              { return __hip_atomic_load(p, __ATOMIC_RELAXED, __HIP_MEMORY_SCOPE_AGENT); }
; __device__ __forceinline__ unsigned xb_add(unsigned* p, unsigned v) { return __hip_atomic_fetch_add(p, v, __ATOMIC_RELAXED, __HIP_MEMORY_SCOPE_AGENT); }
; #define XB_SPIN(cond, bar) do { unsigned _sp = 0; while (cond) { __builtin_amdgcn_s_sleep(1); \
;     if ((++_sp & 255u) == 0u) { if (xb_ld(&(bar)[XB_TMO])) break; if (_sp > XB_SPIN_CAP) { atomicAdd(&(bar)[XB_TMO], 1u); break; } } } } while (0)
; __device__ __forceinline__ void xcd_barrier(const XcdBarrier& b) {
;     ...
;         const unsigned old = xb_add(&bar[XB_XSUB(b.x)], 1u);
;         const unsigned gen = old / nloc;
;         if (old + 1u == (gen + 1u) * nloc) {
;             __builtin_amdgcn_fence(__ATOMIC_RELEASE, "agent");
;             asm volatile("s_waitcnt vmcnt(0)" ::: "memory");
;             const unsigned og = xb_add(&bar[XB_TOP], 1u);
;             const unsigned tg = og / nx;
;             if (og + 1u == (tg + 1u) * nx) xb_add(&bar[XB_TOPGEN], 1u);
;             else XB_SPIN(xb_ld(&bar[XB_TOPGEN]) == tg, bar);
;             __builtin_amdgcn_fence(__ATOMIC_ACQUIRE, "agent");
;             xb_add(&bar[XB_XGEN(b.x)], 1u);
;             asm volatile("s_waitcnt vmcnt(0)" ::: "memory");
;         } else {
;             XB_SPIN(xb_ld(&bar[XB_XGEN(b.x)]) == gen, bar);
.LBB0_352:
	v_mov_b32_e32 v1, 1
	global_atomic_add v3, v[186:187], v1, off sc0
	v_cvt_f32_u32_e32 v1, v2
	v_sub_u32_e32 v4, 0, v2
	v_rcp_iflag_f32_e32 v1, v1
	s_nop 0
	v_mul_f32_e32 v1, 0x4f7ffffe, v1
	v_cvt_u32_f32_e32 v1, v1
	v_mul_lo_u32 v4, v4, v1
	v_mul_hi_u32 v4, v1, v4
	v_add_u32_e32 v1, v1, v4
	s_waitcnt vmcnt(0)
	v_mul_hi_u32 v1, v3, v1
	v_mul_lo_u32 v4, v1, v2
	v_sub_u32_e32 v4, v3, v4
	v_add_u32_e32 v5, 1, v1
	v_cmp_ge_u32_e32 vcc, v4, v2
	v_add_u32_e32 v3, 1, v3
	s_nop 0
	v_cndmask_b32_e32 v1, v1, v5, vcc
	v_sub_u32_e32 v5, v4, v2
	v_cndmask_b32_e32 v4, v4, v5, vcc
	v_add_u32_e32 v5, 1, v1
	v_cmp_ge_u32_e32 vcc, v4, v2
	s_nop 1
	v_cndmask_b32_e32 v1, v1, v5, vcc
	v_mul_lo_u32 v4, v2, v1
	v_add_u32_e32 v2, v4, v2
	v_cmp_ne_u32_e32 vcc, v3, v2
	s_and_saveexec_b64 s[2:3], vcc
	s_xor_b64 s[4:5], exec, s[2:3]
	s_cbranch_execz .LBB0_366
	s_waitcnt lgkmcnt(0)
	v_mad_u32_u24 v6, v1, v0, v0
	v_mov_b32_e32 v0, 0
	global_load_dword v0, v0, s[92:93] offset:-256 sc1
	s_waitcnt vmcnt(0)
	v_cmp_lt_u32_e32 vcc, v0, v6
	s_and_saveexec_b64 s[8:9], vcc
	s_cbranch_execz .LBB0_365
	s_mov_b32 s2, 1
	s_mov_b64 s[12:13], 0
	v_mov_b32_e32 v0, 0
	s_branch .LBB0_356

; __device__ __forceinline__ unsigned xb_ld(unsigned* p)              { return __hip_atomic_load(p, __ATOMIC_RELAXED, __HIP_MEMORY_SCOPE_AGENT); }
; #define XB_SPIN(cond, bar) do { unsigned _sp = 0; while (cond) { __builtin_amdgcn_s_sleep(1); \
;     if ((++_sp & 255u) == 0u) { if (xb_ld(&(bar)[XB_TMO])) break; if (_sp > XB_SPIN_CAP) { atomicAdd(&(bar)[XB_TMO], 1u); break; } } } } while (0)
; __device__ __forceinline__ void xcd_barrier(const XcdBarrier& b) {
;     ...
;             XB_SPIN(xb_ld(&bar[XB_XGEN(b.x)]) == gen, bar);
.LBB0_360:
	global_load_dword v2, v0, s[92:93] offset:-256 sc1
	s_add_i32 s2, s2, 1
	s_mov_b64 s[20:21], -1
	s_waitcnt vmcnt(0)
	v_cmp_ge_u32_e32 vcc, v2, v6
	s_orn2_b64 s[16:17], vcc, exec
	s_branch .LBB0_355

; __device__ __forceinline__ unsigned xb_ld(unsigned* p)              { return __hip_atomic_load(p, __ATOMIC_RELAXED, __HIP_MEMORY_SCOPE_AGENT); }
; __device__ __forceinline__ unsigned xb_add(unsigned* p, unsigned v) { return __hip_atomic_fetch_add(p, v, __ATOMIC_RELAXED, __HIP_MEMORY_SCOPE_AGENT); }
; #define XB_SPIN(cond, bar) do { unsigned _sp = 0; while (cond) { __builtin_amdgcn_s_sleep(1); \
;     if ((++_sp & 255u) == 0u) { if (xb_ld(&(bar)[XB_TMO])) break; if (_sp > XB_SPIN_CAP) { atomicAdd(&(bar)[XB_TMO], 1u); break; } } } } while (0)
; __device__ __forceinline__ void xcd_barrier(const XcdBarrier& b) {
;     ...
;         if (old + 1u == (gen + 1u) * nloc) {
;             __builtin_amdgcn_fence(__ATOMIC_RELEASE, "agent");
;             asm volatile("s_waitcnt vmcnt(0)" ::: "memory");
;             const unsigned og = xb_add(&bar[XB_TOP], 1u);
;             const unsigned tg = og / nx;
;             if (og + 1u == (tg + 1u) * nx) xb_add(&bar[XB_TOPGEN], 1u);
;             else XB_SPIN(xb_ld(&bar[XB_TOPGEN]) == tg, bar);
.LBB0_369:
	s_or_b64 exec, exec, s[8:9]
	s_waitcnt vmcnt(0)
	v_readfirstlane_b32 s2, v2
	v_cvt_f32_u32_e32 v2, v0
	v_sub_u32_e32 v3, 0, v0
	v_add_u32_e32 v1, s2, v1
	s_mov_b64 s[8:9], 0
	v_rcp_iflag_f32_e32 v2, v2
	s_nop 0
	v_mul_f32_e32 v2, 0x4f7ffffe, v2
	v_cvt_u32_f32_e32 v2, v2
	v_mul_lo_u32 v3, v3, v2
	v_mul_hi_u32 v3, v2, v3
	v_add_u32_e32 v2, v2, v3
	v_mul_hi_u32 v2, v1, v2
	v_mul_lo_u32 v3, v2, v0
	v_sub_u32_e32 v3, v1, v3
	v_cmp_ge_u32_e32 vcc, v3, v0
	v_add_u32_e32 v4, 1, v2
	v_add_u32_e32 v1, 1, v1
	v_cndmask_b32_e32 v2, v2, v4, vcc
	v_sub_u32_e32 v4, v3, v0
	v_cndmask_b32_e32 v3, v3, v4, vcc
	v_cmp_ge_u32_e32 vcc, v3, v0
	v_add_u32_e32 v3, 1, v2
	s_nop 0
	v_cndmask_b32_e32 v2, v2, v3, vcc
	v_mul_lo_u32 v3, v0, v2
	v_add_u32_e32 v0, v3, v0
	v_mov_b32_e32 v6, v0
	v_cmp_ne_u32_e32 vcc, v1, v0
	v_mov_b64_e32 v[0:1], s[92:93]
	s_and_saveexec_b64 s[4:5], vcc
	s_cbranch_execz .LBB0_381
	v_mov_b32_e32 v0, 0
	global_load_dword v1, v0, s[92:93] offset:-256 sc1
	s_mov_b64 s[12:13], 0
	s_waitcnt vmcnt(0)
	v_cmp_lt_u32_e32 vcc, v1, v6
	s_and_saveexec_b64 s[8:9], vcc
	s_cbranch_execz .LBB0_380
	s_mov_b32 s2, 1
	s_branch .LBB0_373

; __device__ __forceinline__ unsigned xb_ld(unsigned* p)              { return __hip_atomic_load(p, __ATOMIC_RELAXED, __HIP_MEMORY_SCOPE_AGENT); }
; #define XB_SPIN(cond, bar) do { unsigned _sp = 0; while (cond) { __builtin_amdgcn_s_sleep(1); \
;     if ((++_sp & 255u) == 0u) { if (xb_ld(&(bar)[XB_TMO])) break; if (_sp > XB_SPIN_CAP) { atomicAdd(&(bar)[XB_TMO], 1u); break; } } } } while (0)
; __device__ __forceinline__ void xcd_barrier(const XcdBarrier& b) {
;     ...
;             else XB_SPIN(xb_ld(&bar[XB_TOPGEN]) == tg, bar);
.LBB0_377:
	global_load_dword v1, v0, s[92:93] offset:-256 sc1
	s_add_i32 s2, s2, 1
	s_mov_b64 s[16:17], -1
	s_waitcnt vmcnt(0)
	v_cmp_ge_u32_e32 vcc, v1, v6
	s_orn2_b64 s[34:35], vcc, exec
	s_branch .LBB0_372

; __device__ __forceinline__ unsigned xb_ld(unsigned* p)              { return __hip_atomic_load(p, __ATOMIC_RELAXED, __HIP_MEMORY_SCOPE_AGENT); }
; #define XB_SPIN(cond, bar) do { unsigned _sp = 0; while (cond) { __builtin_amdgcn_s_sleep(1); \
;     if ((++_sp & 255u) == 0u) { if (xb_ld(&(bar)[XB_TMO])) break; if (_sp > XB_SPIN_CAP) { atomicAdd(&(bar)[XB_TMO], 1u); break; } } } } while (0)
; __device__ __forceinline__ void xcd_barrier(const XcdBarrier& b) {
;     ...
;             XB_SPIN(xb_ld(&bar[XB_XGEN(b.x)]) == gen, bar);
.LBB0_437:
	global_load_dword v2, v0, s[92:93] offset:-256 sc1
	s_add_i32 s2, s2, 1
	s_mov_b64 s[22:23], -1
	s_waitcnt vmcnt(0)
	v_cmp_ge_u32_e32 vcc, v2, v6
	s_orn2_b64 s[16:17], vcc, exec
	s_branch .LBB0_432

; __device__ __forceinline__ unsigned xb_ld(unsigned* p)              { return __hip_atomic_load(p, __ATOMIC_RELAXED, __HIP_MEMORY_SCOPE_AGENT); }
; #define XB_SPIN(cond, bar) do { unsigned _sp = 0; while (cond) { __builtin_amdgcn_s_sleep(1); \
;     if ((++_sp & 255u) == 0u) { if (xb_ld(&(bar)[XB_TMO])) break; if (_sp > XB_SPIN_CAP) { atomicAdd(&(bar)[XB_TMO], 1u); break; } } } } while (0)
; __device__ __forceinline__ void xcd_barrier(const XcdBarrier& b) {
;     ...
;             else XB_SPIN(xb_ld(&bar[XB_TOPGEN]) == tg, bar);
.LBB0_454:
	global_load_dword v1, v0, s[92:93] offset:-256 sc1
	s_add_i32 s2, s2, 1
	s_mov_b64 s[16:17], -1
	s_waitcnt vmcnt(0)
	v_cmp_ge_u32_e32 vcc, v1, v6
	s_orn2_b64 s[36:37], vcc, exec
	s_branch .LBB0_449

; __device__ __forceinline__ unsigned xb_ld(unsigned* p)              { return __hip_atomic_load(p, __ATOMIC_RELAXED, __HIP_MEMORY_SCOPE_AGENT); }
; __device__ __forceinline__ unsigned xb_add(unsigned* p, unsigned v) { return __hip_atomic_fetch_add(p, v, __ATOMIC_RELAXED, __HIP_MEMORY_SCOPE_AGENT); }
; #define XB_SPIN(cond, bar) do { unsigned _sp = 0; while (cond) { __builtin_amdgcn_s_sleep(1); \
;     if ((++_sp & 255u) == 0u) { if (xb_ld(&(bar)[XB_TMO])) break; if (_sp > XB_SPIN_CAP) { atomicAdd(&(bar)[XB_TMO], 1u); break; } } } } while (0)
; __device__ __forceinline__ void xcd_barrier(const XcdBarrier& b) {
;     ...
;         const unsigned old = xb_add(&bar[XB_XSUB(b.x)], 1u);
;         const unsigned gen = old / nloc;
;         if (old + 1u == (gen + 1u) * nloc) {
;             __builtin_amdgcn_fence(__ATOMIC_RELEASE, "agent");
;             asm volatile("s_waitcnt vmcnt(0)" ::: "memory");
;             const unsigned og = xb_add(&bar[XB_TOP], 1u);
;             const unsigned tg = og / nx;
;             if (og + 1u == (tg + 1u) * nx) xb_add(&bar[XB_TOPGEN], 1u);
;             else XB_SPIN(xb_ld(&bar[XB_TOPGEN]) == tg, bar);
;             __builtin_amdgcn_fence(__ATOMIC_ACQUIRE, "agent");
;             xb_add(&bar[XB_XGEN(b.x)], 1u);
;             asm volatile("s_waitcnt vmcnt(0)" ::: "memory");
;         } else {
;             XB_SPIN(xb_ld(&bar[XB_XGEN(b.x)]) == gen, bar);
.LBB0_486:
	v_mov_b32_e32 v1, 1
	global_atomic_add v3, v[186:187], v1, off sc0
	v_cvt_f32_u32_e32 v1, v2
	v_sub_u32_e32 v4, 0, v2
	v_rcp_iflag_f32_e32 v1, v1
	s_nop 0
	v_mul_f32_e32 v1, 0x4f7ffffe, v1
	v_cvt_u32_f32_e32 v1, v1
	v_mul_lo_u32 v4, v4, v1
	v_mul_hi_u32 v4, v1, v4
	v_add_u32_e32 v1, v1, v4
	s_waitcnt vmcnt(0)
	v_mul_hi_u32 v1, v3, v1
	v_mul_lo_u32 v4, v1, v2
	v_sub_u32_e32 v4, v3, v4
	v_add_u32_e32 v5, 1, v1
	v_cmp_ge_u32_e32 vcc, v4, v2
	v_add_u32_e32 v3, 1, v3
	s_nop 0
	v_cndmask_b32_e32 v1, v1, v5, vcc
	v_sub_u32_e32 v5, v4, v2
	v_cndmask_b32_e32 v4, v4, v5, vcc
	v_add_u32_e32 v5, 1, v1
	v_cmp_ge_u32_e32 vcc, v4, v2
	s_nop 1
	v_cndmask_b32_e32 v1, v1, v5, vcc
	v_mul_lo_u32 v4, v2, v1
	v_add_u32_e32 v2, v4, v2
	v_cmp_ne_u32_e32 vcc, v3, v2
	s_and_saveexec_b64 s[2:3], vcc
	s_xor_b64 s[8:9], exec, s[2:3]
	s_cbranch_execz .LBB0_500
	s_waitcnt lgkmcnt(0)
	v_mad_u32_u24 v6, v1, v0, v0
	v_mov_b32_e32 v0, 0
	global_load_dword v0, v0, s[92:93] offset:-256 sc1
	s_waitcnt vmcnt(0)
	v_cmp_lt_u32_e32 vcc, v0, v6
	s_and_saveexec_b64 s[12:13], vcc
	s_cbranch_execz .LBB0_499
	s_mov_b32 s2, 1
	s_mov_b64 s[14:15], 0
	v_mov_b32_e32 v0, 0
	s_branch .LBB0_490

; __device__ __forceinline__ unsigned xb_ld(unsigned* p)              { return __hip_atomic_load(p, __ATOMIC_RELAXED, __HIP_MEMORY_SCOPE_AGENT); }
; #define XB_SPIN(cond, bar) do { unsigned _sp = 0; while (cond) { __builtin_amdgcn_s_sleep(1); \
;     if ((++_sp & 255u) == 0u) { if (xb_ld(&(bar)[XB_TMO])) break; if (_sp > XB_SPIN_CAP) { atomicAdd(&(bar)[XB_TMO], 1u); break; } } } } while (0)
; __device__ __forceinline__ void xcd_barrier(const XcdBarrier& b) {
;     ...
;             XB_SPIN(xb_ld(&bar[XB_XGEN(b.x)]) == gen, bar);
.LBB0_494:
	global_load_dword v2, v0, s[92:93] offset:-256 sc1
	s_add_i32 s2, s2, 1
	s_mov_b64 s[36:37], -1
	s_waitcnt vmcnt(0)
	v_cmp_ge_u32_e32 vcc, v2, v6
	s_orn2_b64 s[22:23], vcc, exec
	s_branch .LBB0_489

; __device__ __forceinline__ unsigned xb_ld(unsigned* p)              { return __hip_atomic_load(p, __ATOMIC_RELAXED, __HIP_MEMORY_SCOPE_AGENT); }
; __device__ __forceinline__ unsigned xb_add(unsigned* p, unsigned v) { return __hip_atomic_fetch_add(p, v, __ATOMIC_RELAXED, __HIP_MEMORY_SCOPE_AGENT); }
; #define XB_SPIN(cond, bar) do { unsigned _sp = 0; while (cond) { __builtin_amdgcn_s_sleep(1); \
;     if ((++_sp & 255u) == 0u) { if (xb_ld(&(bar)[XB_TMO])) break; if (_sp > XB_SPIN_CAP) { atomicAdd(&(bar)[XB_TMO], 1u); break; } } } } while (0)
; __device__ __forceinline__ void xcd_barrier(const XcdBarrier& b) {
;     ...
;         if (old + 1u == (gen + 1u) * nloc) {
;             __builtin_amdgcn_fence(__ATOMIC_RELEASE, "agent");
;             asm volatile("s_waitcnt vmcnt(0)" ::: "memory");
;             const unsigned og = xb_add(&bar[XB_TOP], 1u);
;             const unsigned tg = og / nx;
;             if (og + 1u == (tg + 1u) * nx) xb_add(&bar[XB_TOPGEN], 1u);
;             else XB_SPIN(xb_ld(&bar[XB_TOPGEN]) == tg, bar);
.LBB0_503:
	s_or_b64 exec, exec, s[12:13]
	s_waitcnt vmcnt(0)
	v_readfirstlane_b32 s2, v2
	v_cvt_f32_u32_e32 v2, v0
	v_sub_u32_e32 v3, 0, v0
	v_add_u32_e32 v1, s2, v1
	s_mov_b64 s[12:13], 0
	v_rcp_iflag_f32_e32 v2, v2
	s_nop 0
	v_mul_f32_e32 v2, 0x4f7ffffe, v2
	v_cvt_u32_f32_e32 v2, v2
	v_mul_lo_u32 v3, v3, v2
	v_mul_hi_u32 v3, v2, v3
	v_add_u32_e32 v2, v2, v3
	v_mul_hi_u32 v2, v1, v2
	v_mul_lo_u32 v3, v2, v0
	v_sub_u32_e32 v3, v1, v3
	v_cmp_ge_u32_e32 vcc, v3, v0
	v_add_u32_e32 v4, 1, v2
	v_add_u32_e32 v1, 1, v1
	v_cndmask_b32_e32 v2, v2, v4, vcc
	v_sub_u32_e32 v4, v3, v0
	v_cndmask_b32_e32 v3, v3, v4, vcc
	v_cmp_ge_u32_e32 vcc, v3, v0
	v_add_u32_e32 v3, 1, v2
	s_nop 0
	v_cndmask_b32_e32 v2, v2, v3, vcc
	v_mul_lo_u32 v3, v0, v2
	v_add_u32_e32 v0, v3, v0
	v_mov_b32_e32 v6, v0
	v_cmp_ne_u32_e32 vcc, v1, v0
	v_mov_b64_e32 v[0:1], s[92:93]
	s_and_saveexec_b64 s[8:9], vcc
	s_cbranch_execz .LBB0_515
	v_mov_b32_e32 v0, 0
	global_load_dword v1, v0, s[92:93] offset:-256 sc1
	s_mov_b64 s[14:15], 0
	s_waitcnt vmcnt(0)
	v_cmp_lt_u32_e32 vcc, v1, v6
	s_and_saveexec_b64 s[12:13], vcc
	s_cbranch_execz .LBB0_514
	s_mov_b32 s2, 1
	s_branch .LBB0_507

; __device__ __forceinline__ unsigned xb_ld(unsigned* p)              { return __hip_atomic_load(p, __ATOMIC_RELAXED, __HIP_MEMORY_SCOPE_AGENT); }
; #define XB_SPIN(cond, bar) do { unsigned _sp = 0; while (cond) { __builtin_amdgcn_s_sleep(1); \
;     if ((++_sp & 255u) == 0u) { if (xb_ld(&(bar)[XB_TMO])) break; if (_sp > XB_SPIN_CAP) { atomicAdd(&(bar)[XB_TMO], 1u); break; } } } } while (0)
; __device__ __forceinline__ void xcd_barrier(const XcdBarrier& b) {
;     ...
;             else XB_SPIN(xb_ld(&bar[XB_TOPGEN]) == tg, bar);
.LBB0_511:
	global_load_dword v1, v0, s[92:93] offset:-256 sc1
	s_add_i32 s2, s2, 1
	s_mov_b64 s[22:23], -1
	s_waitcnt vmcnt(0)
	v_cmp_ge_u32_e32 vcc, v1, v6
	s_orn2_b64 s[38:39], vcc, exec
	s_branch .LBB0_506

; __device__ __forceinline__ unsigned xb_ld(unsigned* p)              { return __hip_atomic_load(p, __ATOMIC_RELAXED, __HIP_MEMORY_SCOPE_AGENT); }
; #define XB_SPIN(cond, bar) do { unsigned _sp = 0; while (cond) { __builtin_amdgcn_s_sleep(1); \
;     if ((++_sp & 255u) == 0u) { if (xb_ld(&(bar)[XB_TMO])) break; if (_sp > XB_SPIN_CAP) { atomicAdd(&(bar)[XB_TMO], 1u); break; } } } } while (0)
; __device__ __forceinline__ void xcd_barrier(const XcdBarrier& b) {
;     ...
;             XB_SPIN(xb_ld(&bar[XB_XGEN(b.x)]) == gen, bar);
.LBB0_569:
	global_load_dword v2, v0, s[92:93] offset:-256 sc1
	s_add_i32 s2, s2, 1
	s_mov_b64 s[34:35], -1
	s_waitcnt vmcnt(0)
	v_cmp_ge_u32_e32 vcc, v2, v6
	s_orn2_b64 s[22:23], vcc, exec
	s_branch .LBB0_564

; __device__ __forceinline__ unsigned xb_ld(unsigned* p)              { return __hip_atomic_load(p, __ATOMIC_RELAXED, __HIP_MEMORY_SCOPE_AGENT); }
; #define XB_SPIN(cond, bar) do { unsigned _sp = 0; while (cond) { __builtin_amdgcn_s_sleep(1); \
;     if ((++_sp & 255u) == 0u) { if (xb_ld(&(bar)[XB_TMO])) break; if (_sp > XB_SPIN_CAP) { atomicAdd(&(bar)[XB_TMO], 1u); break; } } } } while (0)
; __device__ __forceinline__ void xcd_barrier(const XcdBarrier& b) {
;     ...
;             else XB_SPIN(xb_ld(&bar[XB_TOPGEN]) == tg, bar);
.LBB0_586:
	global_load_dword v1, v0, s[92:93] offset:-256 sc1
	s_add_i32 s2, s2, 1
	s_mov_b64 s[22:23], -1
	s_waitcnt vmcnt(0)
	v_cmp_ge_u32_e32 vcc, v1, v6
	s_orn2_b64 s[36:37], vcc, exec
	s_branch .LBB0_581

; __device__ __forceinline__ unsigned xb_ld(unsigned* p)              { return __hip_atomic_load(p, __ATOMIC_RELAXED, __HIP_MEMORY_SCOPE_AGENT); }
; #define XB_SPIN(cond, bar) do { unsigned _sp = 0; while (cond) { __builtin_amdgcn_s_sleep(1); \
;     if ((++_sp & 255u) == 0u) { if (xb_ld(&(bar)[XB_TMO])) break; if (_sp > XB_SPIN_CAP) { atomicAdd(&(bar)[XB_TMO], 1u); break; } } } } while (0)
; __device__ __forceinline__ void xcd_barrier(const XcdBarrier& b) {
;     ...
;             XB_SPIN(xb_ld(&bar[XB_XGEN(b.x)]) == gen, bar);
.LBB0_787:
	global_load_dword v2, v0, s[92:93] offset:-256 sc1
	s_add_i32 s2, s2, 1
	s_mov_b64 s[36:37], -1
	s_waitcnt vmcnt(0)
	v_cmp_ge_u32_e32 vcc, v2, v6
	s_orn2_b64 s[16:17], vcc, exec
	s_branch .LBB0_782

; __device__ __forceinline__ unsigned xb_ld(unsigned* p)              { return __hip_atomic_load(p, __ATOMIC_RELAXED, __HIP_MEMORY_SCOPE_AGENT); }
; #define XB_SPIN(cond, bar) do { unsigned _sp = 0; while (cond) { __builtin_amdgcn_s_sleep(1); \
;     if ((++_sp & 255u) == 0u) { if (xb_ld(&(bar)[XB_TMO])) break; if (_sp > XB_SPIN_CAP) { atomicAdd(&(bar)[XB_TMO], 1u); break; } } } } while (0)
; __device__ __forceinline__ void xcd_barrier(const XcdBarrier& b) {
;     ...
;             else XB_SPIN(xb_ld(&bar[XB_TOPGEN]) == tg, bar);
.LBB0_804:
	global_load_dword v1, v0, s[92:93] offset:-256 sc1
	s_add_i32 s2, s2, 1
	s_mov_b64 s[16:17], -1
	s_waitcnt vmcnt(0)
	v_cmp_ge_u32_e32 vcc, v1, v6
	s_orn2_b64 s[38:39], vcc, exec
	s_branch .LBB0_799

; __device__ __forceinline__ unsigned xb_ld(unsigned* p)              { return __hip_atomic_load(p, __ATOMIC_RELAXED, __HIP_MEMORY_SCOPE_AGENT); }
; #define XB_SPIN(cond, bar) do { unsigned _sp = 0; while (cond) { __builtin_amdgcn_s_sleep(1); \
;     if ((++_sp & 255u) == 0u) { if (xb_ld(&(bar)[XB_TMO])) break; if (_sp > XB_SPIN_CAP) { atomicAdd(&(bar)[XB_TMO], 1u); break; } } } } while (0)
; __device__ __forceinline__ void xcd_barrier(const XcdBarrier& b) {
;     ...
;             else XB_SPIN(xb_ld(&bar[XB_TOPGEN]) == tg, bar);
.LBB0_1011:
	global_load_dword v1, v0, s[92:93] offset:-256 sc1
	s_add_i32 s2, s2, 1
	s_mov_b64 s[16:17], -1
	s_waitcnt vmcnt(0)
	v_cmp_ge_u32_e32 vcc, v1, v6
	s_orn2_b64 s[22:23], vcc, exec
	s_branch .LBB0_1006

; __device__ __forceinline__ unsigned xb_ld(unsigned* p)              { return __hip_atomic_load(p, __ATOMIC_RELAXED, __HIP_MEMORY_SCOPE_AGENT); }
; __device__ __forceinline__ unsigned xb_add(unsigned* p, unsigned v) { return __hip_atomic_fetch_add(p, v, __ATOMIC_RELAXED, __HIP_MEMORY_SCOPE_AGENT); }
; #define XB_SPIN(cond, bar) do { unsigned _sp = 0; while (cond) { __builtin_amdgcn_s_sleep(1); \
;     if ((++_sp & 255u) == 0u) { if (xb_ld(&(bar)[XB_TMO])) break; if (_sp > XB_SPIN_CAP) { atomicAdd(&(bar)[XB_TMO], 1u); break; } } } } while (0)
; __device__ __forceinline__ void xcd_barrier(const XcdBarrier& b) {
;     ...
;         const unsigned old = xb_add(&bar[XB_XSUB(b.x)], 1u);
;         const unsigned gen = old / nloc;
;         if (old + 1u == (gen + 1u) * nloc) {
;             __builtin_amdgcn_fence(__ATOMIC_RELEASE, "agent");
;             asm volatile("s_waitcnt vmcnt(0)" ::: "memory");
;             const unsigned og = xb_add(&bar[XB_TOP], 1u);
;             const unsigned tg = og / nx;
;             if (og + 1u == (tg + 1u) * nx) xb_add(&bar[XB_TOPGEN], 1u);
;             else XB_SPIN(xb_ld(&bar[XB_TOPGEN]) == tg, bar);
;             __builtin_amdgcn_fence(__ATOMIC_ACQUIRE, "agent");
;             xb_add(&bar[XB_XGEN(b.x)], 1u);
;             asm volatile("s_waitcnt vmcnt(0)" ::: "memory");
;         } else {
;             XB_SPIN(xb_ld(&bar[XB_XGEN(b.x)]) == gen, bar);
.LBB0_1112:
	v_mov_b32_e32 v1, 1
	global_atomic_add v3, v[186:187], v1, off sc0
	v_cvt_f32_u32_e32 v1, v2
	v_sub_u32_e32 v4, 0, v2
	v_rcp_iflag_f32_e32 v1, v1
	s_nop 0
	v_mul_f32_e32 v1, 0x4f7ffffe, v1
	v_cvt_u32_f32_e32 v1, v1
	v_mul_lo_u32 v4, v4, v1
	v_mul_hi_u32 v4, v1, v4
	v_add_u32_e32 v1, v1, v4
	s_waitcnt vmcnt(0)
	v_mul_hi_u32 v1, v3, v1
	v_mul_lo_u32 v4, v1, v2
	v_sub_u32_e32 v4, v3, v4
	v_add_u32_e32 v5, 1, v1
	v_cmp_ge_u32_e32 vcc, v4, v2
	v_add_u32_e32 v3, 1, v3
	s_nop 0
	v_cndmask_b32_e32 v1, v1, v5, vcc
	v_sub_u32_e32 v5, v4, v2
	v_cndmask_b32_e32 v4, v4, v5, vcc
	v_add_u32_e32 v5, 1, v1
	v_cmp_ge_u32_e32 vcc, v4, v2
	s_nop 1
	v_cndmask_b32_e32 v1, v1, v5, vcc
	v_mul_lo_u32 v4, v2, v1
	v_add_u32_e32 v2, v4, v2
	v_cmp_ne_u32_e32 vcc, v3, v2
	s_and_saveexec_b64 s[2:3], vcc
	s_xor_b64 s[4:5], exec, s[2:3]
	s_cbranch_execz .LBB0_1126
	s_waitcnt lgkmcnt(0)
	v_mad_u32_u24 v6, v1, v0, v0
	v_mov_b32_e32 v0, 0
	global_load_dword v0, v0, s[92:93] offset:-256 sc1
	s_waitcnt vmcnt(0)
	v_cmp_lt_u32_e32 vcc, v0, v6
	s_and_saveexec_b64 s[6:7], vcc
	s_cbranch_execz .LBB0_1125
	s_mov_b32 s2, 1
	s_mov_b64 s[8:9], 0
	v_mov_b32_e32 v0, 0
	s_branch .LBB0_1116

; __device__ __forceinline__ unsigned xb_ld(unsigned* p)              { return __hip_atomic_load(p, __ATOMIC_RELAXED, __HIP_MEMORY_SCOPE_AGENT); }
; #define XB_SPIN(cond, bar) do { unsigned _sp = 0; while (cond) { __builtin_amdgcn_s_sleep(1); \
;     if ((++_sp & 255u) == 0u) { if (xb_ld(&(bar)[XB_TMO])) break; if (_sp > XB_SPIN_CAP) { atomicAdd(&(bar)[XB_TMO], 1u); break; } } } } while (0)
; __device__ __forceinline__ void xcd_barrier(const XcdBarrier& b) {
;     ...
;             XB_SPIN(xb_ld(&bar[XB_XGEN(b.x)]) == gen, bar);
.LBB0_1120:
	global_load_dword v2, v0, s[92:93] offset:-256 sc1
	s_add_i32 s2, s2, 1
	s_mov_b64 s[16:17], -1
	s_waitcnt vmcnt(0)
	v_cmp_ge_u32_e32 vcc, v2, v6
	s_orn2_b64 s[14:15], vcc, exec
	s_branch .LBB0_1115

; __device__ __forceinline__ unsigned xb_ld(unsigned* p)              { return __hip_atomic_load(p, __ATOMIC_RELAXED, __HIP_MEMORY_SCOPE_AGENT); }
; __device__ __forceinline__ unsigned xb_add(unsigned* p, unsigned v) { return __hip_atomic_fetch_add(p, v, __ATOMIC_RELAXED, __HIP_MEMORY_SCOPE_AGENT); }
; #define XB_SPIN(cond, bar) do { unsigned _sp = 0; while (cond) { __builtin_amdgcn_s_sleep(1); \
;     if ((++_sp & 255u) == 0u) { if (xb_ld(&(bar)[XB_TMO])) break; if (_sp > XB_SPIN_CAP) { atomicAdd(&(bar)[XB_TMO], 1u); break; } } } } while (0)
; __device__ __forceinline__ void xcd_barrier(const XcdBarrier& b) {
;     ...
;         if (old + 1u == (gen + 1u) * nloc) {
;             __builtin_amdgcn_fence(__ATOMIC_RELEASE, "agent");
;             asm volatile("s_waitcnt vmcnt(0)" ::: "memory");
;             const unsigned og = xb_add(&bar[XB_TOP], 1u);
;             const unsigned tg = og / nx;
;             if (og + 1u == (tg + 1u) * nx) xb_add(&bar[XB_TOPGEN], 1u);
;             else XB_SPIN(xb_ld(&bar[XB_TOPGEN]) == tg, bar);
.LBB0_1129:
	s_or_b64 exec, exec, s[6:7]
	s_waitcnt vmcnt(0)
	v_readfirstlane_b32 s2, v2
	v_cvt_f32_u32_e32 v2, v0
	v_sub_u32_e32 v3, 0, v0
	v_add_u32_e32 v1, s2, v1
	s_mov_b64 s[6:7], 0
	v_rcp_iflag_f32_e32 v2, v2
	s_nop 0
	v_mul_f32_e32 v2, 0x4f7ffffe, v2
	v_cvt_u32_f32_e32 v2, v2
	v_mul_lo_u32 v3, v3, v2
	v_mul_hi_u32 v3, v2, v3
	v_add_u32_e32 v2, v2, v3
	v_mul_hi_u32 v2, v1, v2
	v_mul_lo_u32 v3, v2, v0
	v_sub_u32_e32 v3, v1, v3
	v_cmp_ge_u32_e32 vcc, v3, v0
	v_add_u32_e32 v4, 1, v2
	v_add_u32_e32 v1, 1, v1
	v_cndmask_b32_e32 v2, v2, v4, vcc
	v_sub_u32_e32 v4, v3, v0
	v_cndmask_b32_e32 v3, v3, v4, vcc
	v_cmp_ge_u32_e32 vcc, v3, v0
	v_add_u32_e32 v3, 1, v2
	s_nop 0
	v_cndmask_b32_e32 v2, v2, v3, vcc
	v_mul_lo_u32 v3, v0, v2
	v_add_u32_e32 v0, v3, v0
	v_mov_b32_e32 v6, v0
	v_cmp_ne_u32_e32 vcc, v1, v0
	v_mov_b64_e32 v[0:1], s[92:93]
	s_and_saveexec_b64 s[4:5], vcc
	s_cbranch_execz .LBB0_1141
	v_mov_b32_e32 v0, 0
	global_load_dword v1, v0, s[92:93] offset:-256 sc1
	s_mov_b64 s[8:9], 0
	s_waitcnt vmcnt(0)
	v_cmp_lt_u32_e32 vcc, v1, v6
	s_and_saveexec_b64 s[6:7], vcc
	s_cbranch_execz .LBB0_1140
	s_mov_b32 s2, 1
	s_branch .LBB0_1133

; __device__ __forceinline__ unsigned xb_ld(unsigned* p)              { return __hip_atomic_load(p, __ATOMIC_RELAXED, __HIP_MEMORY_SCOPE_AGENT); }
; #define XB_SPIN(cond, bar) do { unsigned _sp = 0; while (cond) { __builtin_amdgcn_s_sleep(1); \
;     if ((++_sp & 255u) == 0u) { if (xb_ld(&(bar)[XB_TMO])) break; if (_sp > XB_SPIN_CAP) { atomicAdd(&(bar)[XB_TMO], 1u); break; } } } } while (0)
; __device__ __forceinline__ void xcd_barrier(const XcdBarrier& b) {
;     ...
;             else XB_SPIN(xb_ld(&bar[XB_TOPGEN]) == tg, bar);
.LBB0_1137:
	global_load_dword v1, v0, s[92:93] offset:-256 sc1
	s_add_i32 s2, s2, 1
	s_mov_b64 s[14:15], -1
	s_waitcnt vmcnt(0)
	v_cmp_ge_u32_e32 vcc, v1, v6
	s_orn2_b64 s[20:21], vcc, exec
	s_branch .LBB0_1132

; __device__ __forceinline__ unsigned xb_ld(unsigned* p)              { return __hip_atomic_load(p, __ATOMIC_RELAXED, __HIP_MEMORY_SCOPE_AGENT); }
; #define XB_SPIN(cond, bar) do { unsigned _sp = 0; while (cond) { __builtin_amdgcn_s_sleep(1); \
;     if ((++_sp & 255u) == 0u) { if (xb_ld(&(bar)[XB_TMO])) break; if (_sp > XB_SPIN_CAP) { atomicAdd(&(bar)[XB_TMO], 1u); break; } } } } while (0)
; __device__ __forceinline__ void xcd_barrier(const XcdBarrier& b) {
;     ...
;             XB_SPIN(xb_ld(&bar[XB_XGEN(b.x)]) == gen, bar);
.LBB0_1184:
	global_load_dword v2, v0, s[92:93] offset:-256 sc1
	s_add_i32 s2, s2, 1
	s_mov_b64 s[14:15], -1
	s_waitcnt vmcnt(0)
	v_cmp_ge_u32_e32 vcc, v2, v6
	s_orn2_b64 s[12:13], vcc, exec
	s_branch .LBB0_1179

; __device__ __forceinline__ unsigned xb_ld(unsigned* p)              { return __hip_atomic_load(p, __ATOMIC_RELAXED, __HIP_MEMORY_SCOPE_AGENT); }
; __device__ __forceinline__ unsigned xb_add(unsigned* p, unsigned v) { return __hip_atomic_fetch_add(p, v, __ATOMIC_RELAXED, __HIP_MEMORY_SCOPE_AGENT); }
; #define XB_SPIN(cond, bar) do { unsigned _sp = 0; while (cond) { __builtin_amdgcn_s_sleep(1); \
;     if ((++_sp & 255u) == 0u) { if (xb_ld(&(bar)[XB_TMO])) break; if (_sp > XB_SPIN_CAP) { atomicAdd(&(bar)[XB_TMO], 1u); break; } } } } while (0)
; __device__ __forceinline__ void xcd_barrier(const XcdBarrier& b) {
;     ...
;         const unsigned old = xb_add(&bar[XB_XSUB(b.x)], 1u);
;         const unsigned gen = old / nloc;
;         if (old + 1u == (gen + 1u) * nloc) {
;             __builtin_amdgcn_fence(__ATOMIC_RELEASE, "agent");
;             asm volatile("s_waitcnt vmcnt(0)" ::: "memory");
;             const unsigned og = xb_add(&bar[XB_TOP], 1u);
;             const unsigned tg = og / nx;
;             if (og + 1u == (tg + 1u) * nx) xb_add(&bar[XB_TOPGEN], 1u);
;             else XB_SPIN(xb_ld(&bar[XB_TOPGEN]) == tg, bar);
;             __builtin_amdgcn_fence(__ATOMIC_ACQUIRE, "agent");
;             xb_add(&bar[XB_XGEN(b.x)], 1u);
;             asm volatile("s_waitcnt vmcnt(0)" ::: "memory");
;         } else {
;             XB_SPIN(xb_ld(&bar[XB_XGEN(b.x)]) == gen, bar);
.LBB0_1193:
	s_or_b64 exec, exec, s[6:7]
	v_cvt_f32_u32_e32 v3, v0
	s_waitcnt vmcnt(0)
	v_readfirstlane_b32 s2, v2
	s_mov_b64 s[6:7], 0
	v_rcp_iflag_f32_e32 v3, v3
	v_add_u32_e32 v1, s2, v1
	v_add_u32_e32 v4, 1, v1
	v_mul_f32_e32 v2, 0x4f7ffffe, v3
	v_cvt_u32_f32_e32 v2, v2
	v_sub_u32_e32 v3, 0, v0
	v_mul_lo_u32 v3, v3, v2
	v_mul_hi_u32 v3, v2, v3
	v_add_u32_e32 v2, v2, v3
	v_mul_hi_u32 v2, v1, v2
	v_mul_lo_u32 v3, v2, v0
	v_sub_u32_e32 v1, v1, v3
	v_add_u32_e32 v5, 1, v2
	v_cmp_ge_u32_e32 vcc, v1, v0
	v_sub_u32_e32 v3, v1, v0
	s_nop 0
	v_cndmask_b32_e32 v2, v2, v5, vcc
	v_cndmask_b32_e32 v1, v1, v3, vcc
	v_add_u32_e32 v3, 1, v2
	v_cmp_ge_u32_e32 vcc, v1, v0
	s_nop 1
	v_cndmask_b32_e32 v2, v2, v3, vcc
	v_mul_lo_u32 v1, v0, v2
	v_add_u32_e32 v0, v1, v0
	v_mov_b32_e32 v6, v0
	v_cmp_ne_u32_e32 vcc, v4, v0
	v_mov_b64_e32 v[0:1], s[92:93]
	s_and_saveexec_b64 s[4:5], vcc
	s_cbranch_execz .LBB0_1205
	v_mov_b32_e32 v0, 0
	global_load_dword v1, v0, s[92:93] offset:-256 sc1
	s_mov_b64 s[8:9], 0
	s_waitcnt vmcnt(0)
	v_cmp_lt_u32_e32 vcc, v1, v6
	s_and_saveexec_b64 s[6:7], vcc
	s_cbranch_execz .LBB0_1204
	s_mov_b32 s2, 1
	s_branch .LBB0_1197

; __device__ __forceinline__ unsigned xb_ld(unsigned* p)              { return __hip_atomic_load(p, __ATOMIC_RELAXED, __HIP_MEMORY_SCOPE_AGENT); }
; __device__ __forceinline__ unsigned xb_add(unsigned* p, unsigned v) { return __hip_atomic_fetch_add(p, v, __ATOMIC_RELAXED, __HIP_MEMORY_SCOPE_AGENT); }
; #define XB_SPIN(cond, bar) do { unsigned _sp = 0; while (cond) { __builtin_amdgcn_s_sleep(1); \
;     if ((++_sp & 255u) == 0u) { if (xb_ld(&(bar)[XB_TMO])) break; if (_sp > XB_SPIN_CAP) { atomicAdd(&(bar)[XB_TMO], 1u); break; } } } } while (0)
; __device__ __forceinline__ void xcd_barrier(const XcdBarrier& b) {
;     ...
;             if (og + 1u == (tg + 1u) * nx) xb_add(&bar[XB_TOPGEN], 1u);
;             else XB_SPIN(xb_ld(&bar[XB_TOPGEN]) == tg, bar);
.LBB0_1201:
	global_load_dword v1, v0, s[92:93] offset:-256 sc1
	s_add_i32 s2, s2, 1
	s_mov_b64 s[12:13], -1
	s_waitcnt vmcnt(0)
	v_cmp_ge_u32_e32 vcc, v1, v6
	s_orn2_b64 s[16:17], vcc, exec
	s_branch .LBB0_1196
